# block solve: column loads prefetched 6 columns ahead into a rotating register pool with immediate offsets
# baseline (speedup 1.0000x reference)
.LBB0_216:
	s_and_b64 vcc, exec, s[28:29]
	s_cbranch_vccz .LBB0_236
	s_setprio 2
	v_lshlrev_b32_e32 v3, 2, v1
	v_ashrrev_i32_e32 v33, 7, v1
	s_movk_i32 s6, 0x2080
	v_and_b32_e32 v32, 12, v3
	v_ashrrev_i32_e32 v14, 2, v1
	v_mul_lo_u32 v2, v33, s6
	v_lshlrev_b32_e32 v19, 2, v32
	v_readlane_b32 s6, v253, 51
	v_and_b32_e32 v15, 31, v14
	v_cmp_eq_u32_e32 vcc, v32, v15
	v_add3_u32 v6, s6, v2, v19
	ds_read_b128 v[150:153], v6
	ds_read_b128 v[154:157], v6 offset:64
	ds_read_b128 v[158:161], v6 offset:256
	ds_read_b128 v[162:165], v6 offset:320
	ds_read_b128 v[166:169], v6 offset:512
	ds_read_b128 v[170:173], v6 offset:576
	ds_read_b128 v[174:177], v6 offset:768
	ds_read_b128 v[178:181], v6 offset:832
	ds_read_b128 v[182:185], v6 offset:1024
	ds_read_b128 v[186:189], v6 offset:1088
	ds_read_b128 v[190:193], v6 offset:1280
	ds_read_b128 v[194:197], v6 offset:1344
	v_cndmask_b32_e64 v12, 0, 1.0, vcc
	v_or_b32_e32 v31, 1, v32
	v_cmp_eq_u32_e32 vcc, v31, v15
	v_or_b32_e32 v30, 2, v32
	s_nop 0
	v_cndmask_b32_e64 v13, 0, 1.0, vcc
	v_cmp_eq_u32_e32 vcc, v30, v15
	v_or_b32_e32 v29, 3, v32
	v_or_b32_e32 v28, 16, v32
	v_cndmask_b32_e64 v16, 0, 1.0, vcc
	v_cmp_eq_u32_e32 vcc, v29, v15
	s_waitcnt vmcnt(1)
	s_nop 0
	v_cndmask_b32_e64 v17, 0, 1.0, vcc
	v_cmp_eq_u32_e32 vcc, v28, v15
	v_or_b32_e32 v27, 17, v32
	v_or_b32_e32 v26, 18, v32
	v_cndmask_b32_e64 v22, 0, 1.0, vcc
	v_cmp_eq_u32_e32 vcc, v27, v15
	s_nop 1
	v_cndmask_b32_e64 v23, 0, 1.0, vcc
	v_cmp_eq_u32_e32 vcc, v26, v15
	v_or_b32_e32 v21, 19, v32
	s_nop 0
	v_cndmask_b32_e64 v114, 0, 1.0, vcc
	v_cmp_eq_u32_e32 vcc, v21, v15
	v_mov_b32_dpp v18, v12 quad_perm:[0,0,0,0] row_mask:0xf bank_mask:0xf
	s_nop 0
	v_cndmask_b32_e64 v115, 0, 1.0, vcc
	s_waitcnt lgkmcnt(11)
	v_pk_fma_f32 v[12:13], v[150:151], v[18:19], v[12:13] op_sel_hi:[1,0,1] neg_lo:[0,1,0] neg_hi:[0,1,0]
	v_pk_fma_f32 v[16:17], v[152:153], v[18:19], v[16:17] op_sel_hi:[1,0,1] neg_lo:[0,1,0] neg_hi:[0,1,0]
	ds_read_b128 v[150:153], v6 offset:1536
	s_waitcnt lgkmcnt(11)
	v_pk_fma_f32 v[22:23], v[154:155], v[18:19], v[22:23] op_sel_hi:[1,0,1] neg_lo:[0,1,0] neg_hi:[0,1,0]
	v_pk_fma_f32 v[114:115], v[156:157], v[18:19], v[114:115] op_sel_hi:[1,0,1] neg_lo:[0,1,0] neg_hi:[0,1,0]
	ds_read_b128 v[154:157], v6 offset:1600
	v_mov_b32_e32 v20, v131
	v_readlane_b32 s6, v253, 52
	v_mov_b32_dpp v18, v13 quad_perm:[0,0,0,0] row_mask:0xf bank_mask:0xf
	s_waitcnt lgkmcnt(11)
	v_pk_fma_f32 v[16:17], v[160:161], v[18:19], v[16:17] op_sel_hi:[1,0,1] neg_lo:[0,1,0] neg_hi:[0,1,0]
	v_pk_fma_f32 v[12:13], v[158:159], v[18:19], v[12:13] op_sel_hi:[1,0,1] neg_lo:[0,1,0] neg_hi:[0,1,0]
	ds_read_b128 v[158:161], v6 offset:1792
	s_waitcnt lgkmcnt(11)
	v_pk_fma_f32 v[114:115], v[164:165], v[18:19], v[114:115] op_sel_hi:[1,0,1] neg_lo:[0,1,0] neg_hi:[0,1,0]
	v_pk_fma_f32 v[22:23], v[162:163], v[18:19], v[22:23] op_sel_hi:[1,0,1] neg_lo:[0,1,0] neg_hi:[0,1,0]
	ds_read_b128 v[162:165], v6 offset:1856
	s_movk_i32 s8, 0x48
	v_cmp_eq_u32_e32 vcc, 1, v33
	v_mov_b32_dpp v18, v16 quad_perm:[0,0,0,0] row_mask:0xf bank_mask:0xf
	s_waitcnt lgkmcnt(11)
	v_pk_fma_f32 v[16:17], v[168:169], v[18:19], v[16:17] op_sel_hi:[1,0,1] neg_lo:[0,1,0] neg_hi:[0,1,0]
	v_pk_fma_f32 v[12:13], v[166:167], v[18:19], v[12:13] op_sel_hi:[1,0,1] neg_lo:[0,1,0] neg_hi:[0,1,0]
	ds_read_b128 v[166:169], v6 offset:2048
	s_waitcnt lgkmcnt(11)
	v_pk_fma_f32 v[114:115], v[172:173], v[18:19], v[114:115] op_sel_hi:[1,0,1] neg_lo:[0,1,0] neg_hi:[0,1,0]
	v_pk_fma_f32 v[22:23], v[170:171], v[18:19], v[22:23] op_sel_hi:[1,0,1] neg_lo:[0,1,0] neg_hi:[0,1,0]
	ds_read_b128 v[170:173], v6 offset:2112
	v_mov_b32_dpp v18, v17 quad_perm:[0,0,0,0] row_mask:0xf bank_mask:0xf
	s_waitcnt lgkmcnt(11)
	v_pk_fma_f32 v[12:13], v[174:175], v[18:19], v[12:13] op_sel_hi:[1,0,1] neg_lo:[0,1,0] neg_hi:[0,1,0]
	v_pk_fma_f32 v[16:17], v[176:177], v[18:19], v[16:17] op_sel_hi:[1,0,1] neg_lo:[0,1,0] neg_hi:[0,1,0]
	ds_read_b128 v[174:177], v6 offset:2304
	s_waitcnt lgkmcnt(11)
	v_pk_fma_f32 v[114:115], v[180:181], v[18:19], v[114:115] op_sel_hi:[1,0,1] neg_lo:[0,1,0] neg_hi:[0,1,0]
	v_pk_fma_f32 v[22:23], v[178:179], v[18:19], v[22:23] op_sel_hi:[1,0,1] neg_lo:[0,1,0] neg_hi:[0,1,0]
	ds_read_b128 v[178:181], v6 offset:2368
	v_mov_b32_dpp v18, v12 quad_perm:[1,1,1,1] row_mask:0xf bank_mask:0xf
	s_waitcnt lgkmcnt(11)
	v_pk_fma_f32 v[12:13], v[182:183], v[18:19], v[12:13] op_sel_hi:[1,0,1] neg_lo:[0,1,0] neg_hi:[0,1,0]
	v_pk_fma_f32 v[16:17], v[184:185], v[18:19], v[16:17] op_sel_hi:[1,0,1] neg_lo:[0,1,0] neg_hi:[0,1,0]
	ds_read_b128 v[182:185], v6 offset:2560
	s_waitcnt lgkmcnt(11)
	v_pk_fma_f32 v[22:23], v[186:187], v[18:19], v[22:23] op_sel_hi:[1,0,1] neg_lo:[0,1,0] neg_hi:[0,1,0]
	v_pk_fma_f32 v[114:115], v[188:189], v[18:19], v[114:115] op_sel_hi:[1,0,1] neg_lo:[0,1,0] neg_hi:[0,1,0]
	ds_read_b128 v[186:189], v6 offset:2624
	v_mov_b32_dpp v18, v13 quad_perm:[1,1,1,1] row_mask:0xf bank_mask:0xf
	s_waitcnt lgkmcnt(11)
	v_pk_fma_f32 v[16:17], v[192:193], v[18:19], v[16:17] op_sel_hi:[1,0,1] neg_lo:[0,1,0] neg_hi:[0,1,0]
	v_pk_fma_f32 v[12:13], v[190:191], v[18:19], v[12:13] op_sel_hi:[1,0,1] neg_lo:[0,1,0] neg_hi:[0,1,0]
	ds_read_b128 v[190:193], v6 offset:2816
	s_waitcnt lgkmcnt(11)
	v_pk_fma_f32 v[114:115], v[196:197], v[18:19], v[114:115] op_sel_hi:[1,0,1] neg_lo:[0,1,0] neg_hi:[0,1,0]
	v_pk_fma_f32 v[22:23], v[194:195], v[18:19], v[22:23] op_sel_hi:[1,0,1] neg_lo:[0,1,0] neg_hi:[0,1,0]
	ds_read_b128 v[194:197], v6 offset:2880
	v_mov_b32_dpp v18, v16 quad_perm:[1,1,1,1] row_mask:0xf bank_mask:0xf
	s_waitcnt lgkmcnt(11)
	v_pk_fma_f32 v[16:17], v[152:153], v[18:19], v[16:17] op_sel_hi:[1,0,1] neg_lo:[0,1,0] neg_hi:[0,1,0]
	v_pk_fma_f32 v[12:13], v[150:151], v[18:19], v[12:13] op_sel_hi:[1,0,1] neg_lo:[0,1,0] neg_hi:[0,1,0]
	ds_read_b128 v[150:153], v6 offset:3072
	s_waitcnt lgkmcnt(11)
	v_pk_fma_f32 v[22:23], v[154:155], v[18:19], v[22:23] op_sel_hi:[1,0,1] neg_lo:[0,1,0] neg_hi:[0,1,0]
	v_pk_fma_f32 v[114:115], v[156:157], v[18:19], v[114:115] op_sel_hi:[1,0,1] neg_lo:[0,1,0] neg_hi:[0,1,0]
	ds_read_b128 v[154:157], v6 offset:3136
	v_mov_b32_dpp v18, v17 quad_perm:[1,1,1,1] row_mask:0xf bank_mask:0xf
	s_waitcnt lgkmcnt(11)
	v_pk_fma_f32 v[12:13], v[158:159], v[18:19], v[12:13] op_sel_hi:[1,0,1] neg_lo:[0,1,0] neg_hi:[0,1,0]
	v_pk_fma_f32 v[16:17], v[160:161], v[18:19], v[16:17] op_sel_hi:[1,0,1] neg_lo:[0,1,0] neg_hi:[0,1,0]
	ds_read_b128 v[158:161], v6 offset:3328
	s_waitcnt lgkmcnt(11)
	v_pk_fma_f32 v[114:115], v[164:165], v[18:19], v[114:115] op_sel_hi:[1,0,1] neg_lo:[0,1,0] neg_hi:[0,1,0]
	v_pk_fma_f32 v[22:23], v[162:163], v[18:19], v[22:23] op_sel_hi:[1,0,1] neg_lo:[0,1,0] neg_hi:[0,1,0]
	ds_read_b128 v[162:165], v6 offset:3392
	v_mov_b32_dpp v18, v12 quad_perm:[2,2,2,2] row_mask:0xf bank_mask:0xf
	s_waitcnt lgkmcnt(11)
	v_pk_fma_f32 v[12:13], v[166:167], v[18:19], v[12:13] op_sel_hi:[1,0,1] neg_lo:[0,1,0] neg_hi:[0,1,0]
	v_pk_fma_f32 v[16:17], v[168:169], v[18:19], v[16:17] op_sel_hi:[1,0,1] neg_lo:[0,1,0] neg_hi:[0,1,0]
	ds_read_b128 v[166:169], v6 offset:3584
	s_waitcnt lgkmcnt(11)
	v_pk_fma_f32 v[22:23], v[170:171], v[18:19], v[22:23] op_sel_hi:[1,0,1] neg_lo:[0,1,0] neg_hi:[0,1,0]
	v_pk_fma_f32 v[114:115], v[172:173], v[18:19], v[114:115] op_sel_hi:[1,0,1] neg_lo:[0,1,0] neg_hi:[0,1,0]
	ds_read_b128 v[170:173], v6 offset:3648
	v_mov_b32_dpp v18, v13 quad_perm:[2,2,2,2] row_mask:0xf bank_mask:0xf
	s_waitcnt lgkmcnt(11)
	v_pk_fma_f32 v[16:17], v[176:177], v[18:19], v[16:17] op_sel_hi:[1,0,1] neg_lo:[0,1,0] neg_hi:[0,1,0]
	v_pk_fma_f32 v[12:13], v[174:175], v[18:19], v[12:13] op_sel_hi:[1,0,1] neg_lo:[0,1,0] neg_hi:[0,1,0]
	ds_read_b128 v[174:177], v6 offset:3840
	s_waitcnt lgkmcnt(11)
	v_pk_fma_f32 v[114:115], v[180:181], v[18:19], v[114:115] op_sel_hi:[1,0,1] neg_lo:[0,1,0] neg_hi:[0,1,0]
	v_pk_fma_f32 v[22:23], v[178:179], v[18:19], v[22:23] op_sel_hi:[1,0,1] neg_lo:[0,1,0] neg_hi:[0,1,0]
	ds_read_b128 v[178:181], v6 offset:3904
	v_mov_b32_dpp v18, v16 quad_perm:[2,2,2,2] row_mask:0xf bank_mask:0xf
	s_waitcnt lgkmcnt(11)
	v_pk_fma_f32 v[16:17], v[184:185], v[18:19], v[16:17] op_sel_hi:[1,0,1] neg_lo:[0,1,0] neg_hi:[0,1,0]
	v_pk_fma_f32 v[12:13], v[182:183], v[18:19], v[12:13] op_sel_hi:[1,0,1] neg_lo:[0,1,0] neg_hi:[0,1,0]
	ds_read_b128 v[182:185], v6 offset:4160
	s_waitcnt lgkmcnt(11)
	v_pk_fma_f32 v[22:23], v[186:187], v[18:19], v[22:23] op_sel_hi:[1,0,1] neg_lo:[0,1,0] neg_hi:[0,1,0]
	v_pk_fma_f32 v[114:115], v[188:189], v[18:19], v[114:115] op_sel_hi:[1,0,1] neg_lo:[0,1,0] neg_hi:[0,1,0]
	ds_read_b128 v[186:189], v6 offset:4416
	v_mov_b32_dpp v18, v17 quad_perm:[2,2,2,2] row_mask:0xf bank_mask:0xf
	s_waitcnt lgkmcnt(11)
	v_pk_fma_f32 v[12:13], v[190:191], v[18:19], v[12:13] op_sel_hi:[1,0,1] neg_lo:[0,1,0] neg_hi:[0,1,0]
	v_pk_fma_f32 v[16:17], v[192:193], v[18:19], v[16:17] op_sel_hi:[1,0,1] neg_lo:[0,1,0] neg_hi:[0,1,0]
	ds_read_b128 v[190:193], v6 offset:4672
	s_waitcnt lgkmcnt(11)
	v_pk_fma_f32 v[114:115], v[196:197], v[18:19], v[114:115] op_sel_hi:[1,0,1] neg_lo:[0,1,0] neg_hi:[0,1,0]
	v_pk_fma_f32 v[22:23], v[194:195], v[18:19], v[22:23] op_sel_hi:[1,0,1] neg_lo:[0,1,0] neg_hi:[0,1,0]
	ds_read_b128 v[194:197], v6 offset:4928
	v_mov_b32_dpp v18, v12 quad_perm:[3,3,3,3] row_mask:0xf bank_mask:0xf
	s_waitcnt lgkmcnt(11)
	v_pk_fma_f32 v[12:13], v[150:151], v[18:19], v[12:13] op_sel_hi:[1,0,1] neg_lo:[0,1,0] neg_hi:[0,1,0]
	v_pk_fma_f32 v[16:17], v[152:153], v[18:19], v[16:17] op_sel_hi:[1,0,1] neg_lo:[0,1,0] neg_hi:[0,1,0]
	ds_read_b128 v[150:153], v6 offset:5184
	s_waitcnt lgkmcnt(11)
	v_pk_fma_f32 v[22:23], v[154:155], v[18:19], v[22:23] op_sel_hi:[1,0,1] neg_lo:[0,1,0] neg_hi:[0,1,0]
	v_pk_fma_f32 v[114:115], v[156:157], v[18:19], v[114:115] op_sel_hi:[1,0,1] neg_lo:[0,1,0] neg_hi:[0,1,0]
	ds_read_b128 v[154:157], v6 offset:5440
	v_mov_b32_dpp v18, v13 quad_perm:[3,3,3,3] row_mask:0xf bank_mask:0xf
	s_waitcnt lgkmcnt(11)
	v_pk_fma_f32 v[16:17], v[160:161], v[18:19], v[16:17] op_sel_hi:[1,0,1] neg_lo:[0,1,0] neg_hi:[0,1,0]
	v_pk_fma_f32 v[12:13], v[158:159], v[18:19], v[12:13] op_sel_hi:[1,0,1] neg_lo:[0,1,0] neg_hi:[0,1,0]
	ds_read_b128 v[158:161], v6 offset:5696
	s_waitcnt lgkmcnt(11)
	v_pk_fma_f32 v[104:105], v[164:165], v[18:19], v[114:115] op_sel_hi:[1,0,1] neg_lo:[0,1,0] neg_hi:[0,1,0]
	v_pk_fma_f32 v[22:23], v[162:163], v[18:19], v[22:23] op_sel_hi:[1,0,1] neg_lo:[0,1,0] neg_hi:[0,1,0]
	ds_read_b128 v[162:165], v6 offset:5952
	v_mov_b32_dpp v18, v16 quad_perm:[3,3,3,3] row_mask:0xf bank_mask:0xf
	s_waitcnt lgkmcnt(11)
	v_pk_fma_f32 v[16:17], v[168:169], v[18:19], v[16:17] op_sel_hi:[1,0,1] neg_lo:[0,1,0] neg_hi:[0,1,0]
	v_pk_fma_f32 v[114:115], v[166:167], v[18:19], v[12:13] op_sel_hi:[1,0,1] neg_lo:[0,1,0] neg_hi:[0,1,0]
	ds_read_b128 v[166:169], v6 offset:6208
	s_waitcnt lgkmcnt(11)
	v_pk_fma_f32 v[12:13], v[170:171], v[18:19], v[22:23] op_sel_hi:[1,0,1] neg_lo:[0,1,0] neg_hi:[0,1,0]
	v_pk_fma_f32 v[22:23], v[172:173], v[18:19], v[104:105] op_sel_hi:[1,0,1] neg_lo:[0,1,0] neg_hi:[0,1,0]
	ds_read_b128 v[170:173], v6 offset:6464
	v_mov_b32_dpp v18, v17 quad_perm:[3,3,3,3] row_mask:0xf bank_mask:0xf
	s_waitcnt lgkmcnt(10)
	v_pk_fma_f32 v[12:13], v[178:179], v[18:19], v[12:13] op_sel_hi:[1,0,1] neg_lo:[0,1,0] neg_hi:[0,1,0]
	v_pk_fma_f32 v[22:23], v[180:181], v[18:19], v[22:23] op_sel_hi:[1,0,1] neg_lo:[0,1,0] neg_hi:[0,1,0]
	ds_read_b128 v[178:181], v6 offset:6720
	v_mov_b32_e32 v7, v12
	v_pk_fma_f32 v[2:3], v[174:175], v[18:19], v[114:115] op_sel_hi:[1,0,1] neg_lo:[0,1,0] neg_hi:[0,1,0]
	s_nop 0
	v_mov_b32_dpp v20, v7 quad_perm:[0,0,0,0] row_mask:0xf bank_mask:0xf
	s_waitcnt lgkmcnt(10)
	v_pk_fma_f32 v[12:13], v[182:183], v[20:21], v[12:13] op_sel_hi:[1,0,1] neg_lo:[0,1,0] neg_hi:[0,1,0]
	v_pk_fma_f32 v[22:23], v[184:185], v[20:21], v[22:23] op_sel_hi:[1,0,1] neg_lo:[0,1,0] neg_hi:[0,1,0]
	ds_read_b128 v[182:185], v6 offset:6976
	v_mov_b32_dpp v20, v13 quad_perm:[0,0,0,0] row_mask:0xf bank_mask:0xf
	s_waitcnt lgkmcnt(10)
	v_pk_fma_f32 v[22:23], v[188:189], v[20:21], v[22:23] op_sel_hi:[1,0,1] neg_lo:[0,1,0] neg_hi:[0,1,0]
	v_pk_fma_f32 v[12:13], v[186:187], v[20:21], v[12:13] op_sel_hi:[1,0,1] neg_lo:[0,1,0] neg_hi:[0,1,0]
	ds_read_b128 v[186:189], v6 offset:7232
	v_mov_b32_e32 v20, v131
	v_mov_b32_e32 v7, v22
	s_nop 1
	v_mov_b32_dpp v20, v7 quad_perm:[0,0,0,0] row_mask:0xf bank_mask:0xf
	s_waitcnt lgkmcnt(10)
	v_pk_fma_f32 v[22:23], v[192:193], v[20:21], v[22:23] op_sel_hi:[1,0,1] neg_lo:[0,1,0] neg_hi:[0,1,0]
	v_pk_fma_f32 v[12:13], v[190:191], v[20:21], v[12:13] op_sel_hi:[1,0,1] neg_lo:[0,1,0] neg_hi:[0,1,0]
	ds_read_b128 v[190:193], v6 offset:7488
	v_mov_b32_e32 v20, v131
	v_mov_b32_e32 v7, v23
	s_nop 1
	v_mov_b32_dpp v20, v7 quad_perm:[0,0,0,0] row_mask:0xf bank_mask:0xf
	s_waitcnt lgkmcnt(10)
	v_pk_fma_f32 v[12:13], v[194:195], v[20:21], v[12:13] op_sel_hi:[1,0,1] neg_lo:[0,1,0] neg_hi:[0,1,0]
	v_pk_fma_f32 v[22:23], v[196:197], v[20:21], v[22:23] op_sel_hi:[1,0,1] neg_lo:[0,1,0] neg_hi:[0,1,0]
	ds_read_b128 v[194:197], v6 offset:7744
	v_mov_b32_dpp v20, v12 quad_perm:[1,1,1,1] row_mask:0xf bank_mask:0xf
	s_waitcnt lgkmcnt(10)
	v_pk_fma_f32 v[12:13], v[150:151], v[20:21], v[12:13] op_sel_hi:[1,0,1] neg_lo:[0,1,0] neg_hi:[0,1,0]
	v_pk_fma_f32 v[22:23], v[152:153], v[20:21], v[22:23] op_sel_hi:[1,0,1] neg_lo:[0,1,0] neg_hi:[0,1,0]
	s_nop 0
	v_mov_b32_dpp v20, v13 quad_perm:[1,1,1,1] row_mask:0xf bank_mask:0xf
	s_waitcnt lgkmcnt(9)
	v_pk_fma_f32 v[22:23], v[156:157], v[20:21], v[22:23] op_sel_hi:[1,0,1] neg_lo:[0,1,0] neg_hi:[0,1,0]
	v_pk_fma_f32 v[12:13], v[154:155], v[20:21], v[12:13] op_sel_hi:[1,0,1] neg_lo:[0,1,0] neg_hi:[0,1,0]
	v_mov_b32_e32 v20, v131
	v_mov_b32_e32 v7, v22
	s_nop 1
	v_mov_b32_dpp v20, v7 quad_perm:[1,1,1,1] row_mask:0xf bank_mask:0xf
	s_waitcnt lgkmcnt(8)
	v_pk_fma_f32 v[22:23], v[160:161], v[20:21], v[22:23] op_sel_hi:[1,0,1] neg_lo:[0,1,0] neg_hi:[0,1,0]
	v_pk_fma_f32 v[12:13], v[158:159], v[20:21], v[12:13] op_sel_hi:[1,0,1] neg_lo:[0,1,0] neg_hi:[0,1,0]
	v_mov_b32_e32 v20, v131
	v_mov_b32_e32 v7, v23
	s_nop 1
	v_mov_b32_dpp v20, v7 quad_perm:[1,1,1,1] row_mask:0xf bank_mask:0xf
	s_waitcnt lgkmcnt(7)
	v_pk_fma_f32 v[12:13], v[162:163], v[20:21], v[12:13] op_sel_hi:[1,0,1] neg_lo:[0,1,0] neg_hi:[0,1,0]
	v_pk_fma_f32 v[22:23], v[164:165], v[20:21], v[22:23] op_sel_hi:[1,0,1] neg_lo:[0,1,0] neg_hi:[0,1,0]
	s_nop 0
	v_mov_b32_dpp v20, v12 quad_perm:[2,2,2,2] row_mask:0xf bank_mask:0xf
	s_waitcnt lgkmcnt(6)
	v_pk_fma_f32 v[8:9], v[166:167], v[20:21], v[12:13] op_sel_hi:[1,0,1] neg_lo:[0,1,0] neg_hi:[0,1,0]
	v_mov_b32_e32 v12, v131
	v_mov_b32_e32 v7, v9
	v_pk_fma_f32 v[10:11], v[168:169], v[20:21], v[22:23] op_sel_hi:[1,0,1] neg_lo:[0,1,0] neg_hi:[0,1,0]
	v_mov_b32_e32 v20, v131
	v_mov_b32_dpp v12, v7 quad_perm:[2,2,2,2] row_mask:0xf bank_mask:0xf
	s_waitcnt lgkmcnt(5)
	v_pk_fma_f32 v[10:11], v[172:173], v[12:13], v[10:11] op_sel_hi:[1,0,1] neg_lo:[0,1,0] neg_hi:[0,1,0]
	v_pk_fma_f32 v[8:9], v[170:171], v[12:13], v[8:9] op_sel_hi:[1,0,1] neg_lo:[0,1,0] neg_hi:[0,1,0]
	v_mov_b32_e32 v12, v131
	v_mov_b32_e32 v7, v10
	s_nop 1
	v_mov_b32_dpp v12, v7 quad_perm:[2,2,2,2] row_mask:0xf bank_mask:0xf
	s_waitcnt lgkmcnt(4)
	v_pk_fma_f32 v[22:23], v[180:181], v[12:13], v[10:11] op_sel_hi:[1,0,1] neg_lo:[0,1,0] neg_hi:[0,1,0]
	v_pk_fma_f32 v[8:9], v[178:179], v[12:13], v[8:9] op_sel_hi:[1,0,1] neg_lo:[0,1,0] neg_hi:[0,1,0]
	v_mov_b32_e32 v7, v23
	s_nop 1
	v_mov_b32_dpp v20, v7 quad_perm:[2,2,2,2] row_mask:0xf bank_mask:0xf
	s_waitcnt lgkmcnt(3)
	v_pk_fma_f32 v[102:103], v[182:183], v[20:21], v[8:9] op_sel_hi:[1,0,1] neg_lo:[0,1,0] neg_hi:[0,1,0]
	v_pk_fma_f32 v[22:23], v[184:185], v[20:21], v[22:23] op_sel_hi:[1,0,1] neg_lo:[0,1,0] neg_hi:[0,1,0]
	s_nop 0
	v_mov_b32_dpp v20, v102 quad_perm:[3,3,3,3] row_mask:0xf bank_mask:0xf
	s_waitcnt lgkmcnt(2)
	v_pk_fma_f32 v[100:101], v[188:189], v[20:21], v[22:23] op_sel_hi:[1,0,1] neg_lo:[0,1,0] neg_hi:[0,1,0]
	v_pk_fma_f32 v[22:23], v[186:187], v[20:21], v[102:103] op_sel_hi:[1,0,1] neg_lo:[0,1,0] neg_hi:[0,1,0]
	v_mov_b32_e32 v24, v131
	v_mov_b32_e32 v20, v23
	v_lshlrev_b32_e32 v98, 5, v33
	v_lshl_add_u32 v33, v15, 2, s6
	v_mov_b32_dpp v24, v20 quad_perm:[3,3,3,3] row_mask:0xf bank_mask:0xf
	v_and_b32_e32 v20, -4, v1
	s_waitcnt lgkmcnt(1)
	v_pk_fma_f32 v[12:13], v[192:193], v[24:25], v[100:101] op_sel_hi:[1,0,1] neg_lo:[0,1,0] neg_hi:[0,1,0]
	v_add_u32_e32 v20, 0, v20
	v_mov_b32_e32 v93, v12
	s_waitcnt vmcnt(0)
	v_add_u32_e32 v97, 0x24a00, v20
	v_add_u32_e32 v20, 0x24b00, v20
	ds_read_b32 v97, v97
	ds_read_b32 v99, v20
	v_mov_b32_e32 v20, 0
	s_waitcnt lgkmcnt(1)
	v_mul_f32_e32 v100, v2, v97
	v_mov_b32_dpp v20, v93 quad_perm:[3,3,3,3] row_mask:0xf bank_mask:0xf
	s_waitcnt lgkmcnt(0)
	v_mul_f32_e32 v93, v97, v99
	v_or_b32_e32 v99, v32, v98
	v_cvt_pk_bf16_f32 v102, v100, s0
	v_mad_u64_u32 v[100:101], s[6:7], v99, s8, v[14:15]
	v_lshl_add_u32 v99, v100, 1, 0
	v_add_u32_e32 v100, 0x18000, v99
	ds_write_b16 v100, v102
	v_mul_f32_e32 v100, v2, v93
	v_cvt_pk_bf16_f32 v100, v100, s0
	v_add_u32_e32 v99, 0x1a400, v99
	ds_write_b16 v99, v100
	s_and_saveexec_b64 s[28:29], vcc
	s_cbranch_execz .LBB0_219
	v_mad_u32_u24 v99, v32, s8, v14
	v_lshl_add_u32 v99, v99, 1, 0
	s_movk_i32 s6, 0x90
	v_add_u32_e32 v100, 0x18000, v99
	v_add_u32_e32 v99, 0x1a400, v99
	v_mad_u32_u24 v32, v32, s6, v33
	ds_write_b16 v100, v131
	ds_write_b16 v99, v131
	ds_write_b32 v32, v2
.LBB0_219:
	s_or_b64 exec, exec, s[28:29]
	v_pk_fma_f32 v[4:5], v[176:177], v[18:19], v[16:17] op_sel_hi:[1,0,1] neg_lo:[0,1,0] neg_hi:[0,1,0]
	v_or_b32_e32 v16, v31, v98
	v_mul_f32_e32 v17, v3, v97
	v_cvt_pk_bf16_f32 v18, v17, s0
	v_mad_u64_u32 v[16:17], s[6:7], v16, s8, v[14:15]
	v_lshl_add_u32 v16, v16, 1, 0
	v_add_u32_e32 v17, 0x18000, v16
	ds_write_b16 v17, v18
	v_mul_f32_e32 v17, v3, v93
	v_cvt_pk_bf16_f32 v17, v17, s0
	v_add_u32_e32 v16, 0x1a400, v16
	ds_write_b16 v16, v17
	s_and_saveexec_b64 s[28:29], vcc
	s_cbranch_execz .LBB0_221
	v_mad_u32_u24 v16, v31, s8, v14
	v_lshl_add_u32 v16, v16, 1, 0
	v_add_u32_e32 v17, 0x18000, v16
	v_add_u32_e32 v16, 0x1a400, v16
	s_movk_i32 s6, 0x90
	ds_write_b16 v16, v131
	v_mad_u32_u24 v16, v31, s6, v33
	ds_write_b16 v17, v131
	ds_write_b32 v16, v3

.LBB0_225:
	s_or_b64 exec, exec, s[28:29]
	v_pk_fma_f32 v[10:11], v[190:191], v[24:25], v[22:23] op_sel_hi:[1,0,1] neg_lo:[0,1,0] neg_hi:[0,1,0]
	v_pk_fma_f32 v[6:7], v[194:195], v[20:21], v[10:11] op_sel_hi:[1,0,1] neg_lo:[0,1,0] neg_hi:[0,1,0]
	v_or_b32_e32 v10, v28, v98
	v_mul_f32_e32 v11, v97, v6
	v_cvt_pk_bf16_f32 v16, v11, s0
	v_mad_u64_u32 v[10:11], s[6:7], v10, s8, v[14:15]
	v_lshl_add_u32 v10, v10, 1, 0
	v_add_u32_e32 v11, 0x18000, v10
	ds_write_b16 v11, v16
	v_mul_f32_e32 v11, v93, v6
	v_cvt_pk_bf16_f32 v11, v11, s0
	v_add_u32_e32 v10, 0x1a400, v10
	ds_write_b16 v10, v11
	s_and_saveexec_b64 s[28:29], vcc
	s_cbranch_execz .LBB0_227
	v_mad_u32_u24 v10, v28, s8, v14
	v_lshl_add_u32 v10, v10, 1, 0
	v_add_u32_e32 v11, 0x18000, v10
	v_add_u32_e32 v10, 0x1a400, v10
	s_movk_i32 s6, 0x90
	ds_write_b16 v10, v131
	v_mad_u32_u24 v10, v28, s6, v33
	ds_write_b16 v11, v131
	ds_write_b32 v10, v6
.LBB0_227:
	s_or_b64 exec, exec, s[28:29]
	v_or_b32_e32 v10, v27, v98
	v_mul_f32_e32 v11, v97, v7
	v_pk_fma_f32 v[8:9], v[196:197], v[20:21], v[12:13] op_sel_hi:[1,0,1] neg_lo:[0,1,0] neg_hi:[0,1,0]
	v_cvt_pk_bf16_f32 v12, v11, s0
	v_mad_u64_u32 v[10:11], s[6:7], v10, s8, v[14:15]
	v_lshl_add_u32 v10, v10, 1, 0
	v_add_u32_e32 v11, 0x18000, v10
	ds_write_b16 v11, v12
	v_mul_f32_e32 v11, v93, v7
	v_cvt_pk_bf16_f32 v11, v11, s0
	v_add_u32_e32 v10, 0x1a400, v10
	ds_write_b16 v10, v11
	s_and_saveexec_b64 s[28:29], vcc
	s_cbranch_execz .LBB0_229
	v_mad_u32_u24 v10, v27, s8, v14
	v_lshl_add_u32 v10, v10, 1, 0
	v_add_u32_e32 v11, 0x18000, v10
	v_add_u32_e32 v10, 0x1a400, v10
	s_movk_i32 s6, 0x90
	ds_write_b16 v10, v131
	v_mad_u32_u24 v10, v27, s6, v33
	ds_write_b16 v11, v131
	ds_write_b32 v10, v7
